# one static s_setprio 1 for waves 4-7 during phases 3, 5 and 7 (reset at phase end)
# baseline (speedup 1.0000x reference)
.LBB0_292:
.LBB0_293:
	s_cmp_lt_i32 s68, 4
	s_cselect_b64 s[8:9], -1, 0
	s_and_b64 s[18:19], s[8:9], s[6:7]
	s_andn2_b64 vcc, exec, s[18:19]
	s_cbranch_vccnz .LBB0_510
	s_cmpk_gt_i32 s2, 0x1ff
	s_cbranch_scc1 .LBB0_510
	v_bfe_u32 v113, v1, 5, 1
	v_lshl_or_b32 v3, v1, 8, v1
	v_lshlrev_b32_e32 v4, 14, v113
	s_movk_i32 s8, 0x403
	v_and_or_b32 v121, v3, s8, v4
	v_bfe_u32 v4, v1, 3, 3
	v_and_b32_e32 v2, 63, v1
	v_and_b32_e32 v111, 31, v1
	v_bitop3_b32 v5, v4, v1, 7 bitop3:0x78
	v_lshlrev_b32_e32 v4, 7, v4
	v_and_b32_e32 v3, 7, v1
	v_lshl_or_b32 v106, v5, 4, v4
	v_lshlrev_b32_e32 v4, 7, v111
	v_cmp_lt_u32_e64 s[8:9], 31, v2
	v_bitop3_b32 v2, v113, v1, 7 bitop3:0x78
	v_lshl_or_b32 v154, v2, 4, v4
	v_bitop3_b32 v2, v113, v3, 2 bitop3:0x36
	v_lshl_or_b32 v156, v2, 4, v4
	v_bitop3_b32 v2, v113, v3, 4 bitop3:0x36
	v_lshl_or_b32 v157, v2, 4, v4
	v_bitop3_b32 v2, v113, v3, 6 bitop3:0x36
	v_lshl_or_b32 v158, v2, 4, v4
	v_add_u32_e32 v2, 0x200, v1
	v_mov_b32_e32 v109, 0
	v_lshlrev_b32_e32 v112, 3, v2
	v_lshrrev_b32_e32 v162, 2, v2
	v_lshlrev_b32_e32 v2, 1, v1
	s_movk_i32 s10, 0x80
	v_mov_b32_e32 v107, v109
	v_and_or_b32 v164, v2, s10, v111
	v_lshlrev_b32_e32 v2, 2, v113
	v_lshlrev_b32_e32 v110, 3, v1
	v_lshl_or_b32 v2, v164, 5, v2
	s_add_u32 s97, s66, 0x3c00000
	v_lshl_add_u64 v[4:5], s[66:67], 0, v[106:107]
	s_mov_b64 s[22:23], 0x8000
	s_mov_b32 s0, s3
	v_cmp_gt_u32_e64 s[6:7], 8, v111
	v_lshlrev_b32_e32 v120, 3, v113
	v_or_b32_e32 v122, 0x800, v121
	s_movk_i32 s96, 0x1000
	v_or_b32_e32 v123, 0x1000, v121
	v_or_b32_e32 v124, 0x1800, v121
	v_or_b32_e32 v125, 0x2000, v121
	v_or_b32_e32 v126, 0x2800, v121
	v_or_b32_e32 v127, 0x3000, v121
	v_or_b32_e32 v128, 0x3800, v121
	v_or_b32_e32 v129, 0x8000, v121
	v_or_b32_e32 v130, 0x8800, v121
	v_or_b32_e32 v131, 0x9000, v121
	v_or_b32_e32 v132, 0x9800, v121
	v_or_b32_e32 v133, 0xa000, v121
	v_or_b32_e32 v134, 0xa800, v121
	v_or_b32_e32 v135, 0xb000, v121
	v_or_b32_e32 v136, 0xb800, v121
	v_or_b32_e32 v137, 0x10000, v121
	v_or_b32_e32 v138, 0x10800, v121
	v_or_b32_e32 v139, 0x11000, v121
	v_or_b32_e32 v140, 0x11800, v121
	v_or_b32_e32 v141, 0x12000, v121
	v_or_b32_e32 v142, 0x12800, v121
	v_or_b32_e32 v143, 0x13000, v121
	v_or_b32_e32 v144, 0x13800, v121
	v_or_b32_e32 v145, 0x18000, v121
	v_or_b32_e32 v146, 0x18800, v121
	v_or_b32_e32 v147, 0x19000, v121
	v_or_b32_e32 v148, 0x19800, v121
	v_or_b32_e32 v149, 0x1a000, v121
	v_or_b32_e32 v150, 0x1a800, v121
	v_or_b32_e32 v151, 0x1b000, v121
	v_or_b32_e32 v152, 0x1b800, v121
	v_lshrrev_b32_e32 v153, 6, v1
	v_or_b32_e32 v155, 2, v113
	v_add_u32_e32 v159, 8, v110
	v_lshrrev_b32_e32 v160, 2, v1
	v_add_u32_e32 v161, 8, v112
	v_lshrrev_b32_e32 v163, 7, v1
	s_addc_u32 s3, s67, 0
	v_lshlrev_b32_e32 v165, 1, v111
	s_mov_b32 s21, 0
	v_sub_u32_e32 v166, 0, v111
	v_lshl_add_u64 v[114:115], v[4:5], 0, s[22:23]
	v_lshl_add_u32 v167, v1, 4, 0
	s_movk_i32 s1, 0x100
	s_mov_b32 s74, 0x447fc000
	v_mov_b32_e32 v168, 0xc0447cbd
	s_mov_b32 s75, 0xbfb8aa3b
	s_mov_b32 s76, 0x1a40000
	s_mov_b64 s[24:25], 0x400
	s_mov_b64 s[26:27], 0x800
	s_mov_b64 s[28:29], 0xc00
	s_movk_i32 s77, 0x79c0
	v_mov_b32_e32 v169, 0x4000
	v_mov_b32_e32 v170, 0x7000
	v_mov_b32_e32 v171, 0x5000
	v_mov_b32_e32 v172, 0x8000
	v_lshlrev_b32_e32 v116, 1, v112
	v_mov_b32_e32 v173, 0x3000
	v_mov_b32_e32 v174, 0x6000
	v_lshlrev_b32_e32 v118, 1, v2
	v_mov_b32_e32 v190, v109
	v_mov_b32_e32 v191, v109
	v_mov_b32_e32 v192, v109
	v_mov_b32_e32 v193, v109
	v_cmp_gt_u32_e32 vcc, 0x100, v1
	s_cbranch_vccnz .Lprio_p3
	s_setprio 1
.Lprio_p3:
	s_mov_b32 s78, s2
	s_mov_b32 s32, s70
	s_cmpk_lg_u32 s70, 0x100
	s_cbranch_scc1 .Lp3_order
	s_bitcmp1_b32 s2, 3
	s_cbranch_scc0 .Lp3_order
	s_addk_i32 s78, 0x100
	s_movk_i32 s32, 0xff00

.LBB0_509:
	s_setprio 0
	s_mov_b32 s3, s0

.LBB0_697:
	s_cmp_lt_i32 s68, 6
	s_cselect_b64 s[6:7], -1, 0
	s_and_b64 s[48:49], s[6:7], s[4:5]
	s_andn2_b64 vcc, exec, s[48:49]
	s_cbranch_vccnz .LBB0_754
	s_cmpk_gt_i32 s2, 0x1ff
	s_cbranch_scc1 .LBB0_754
	v_lshrrev_b32_e32 v83, 8, v1
	s_mov_b32 s5, 0x9600
	v_lshrrev_b32_e32 v2, 1, v1
	v_and_b32_e32 v30, 31, v1
	v_mad_u32_u24 v32, v83, s5, 0
	s_movk_i32 s5, 0x60
	v_bfe_u32 v31, v1, 5, 1
	v_and_or_b32 v38, v2, s5, v30
	v_lshlrev_b32_e32 v134, 4, v31
	s_movk_i32 s8, 0x50
	v_lshlrev_b32_e32 v33, 1, v38
	s_movk_i32 s33, 0x110
	s_movk_i32 s4, 0x100
	v_mad_u32_u24 v135, v38, s8, v32
	v_add_u32_e32 v137, v32, v134
	v_add_u32_e32 v41, v32, v33
	v_mad_u32_u24 v140, v30, s33, v32
	v_lshlrev_b32_e32 v32, 2, v31
	s_add_i32 s42, 0, 0x12c00
	v_cmp_gt_u32_e64 s[4:5], s4, v1
	v_add_u32_e32 v86, s42, v33
	v_xor_b32_e32 v33, 31, v32
	v_cndmask_b32_e64 v143, v33, v32, s[4:5]
	v_or_b32_e32 v33, 2, v32
	v_mov_b32_e32 v2, 0xfffffc00
	v_mov_b32_e32 v3, 0x400
	v_cmp_gt_u32_e64 s[12:13], v33, v30
	v_or_b32_e32 v33, 3, v32
	v_cndmask_b32_e64 v87, v2, v3, s[4:5]
	v_xor_b32_e32 v2, 31, v134
	v_mov_b32_e32 v39, 0xe0
	v_cmp_gt_u32_e64 s[14:15], v33, v30
	v_or_b32_e32 v33, 8, v32
	v_cndmask_b32_e64 v3, v39, 0, s[4:5]
	v_cndmask_b32_e64 v40, v2, v134, s[4:5]
	v_cmp_gt_u32_e64 s[16:17], v33, v30
	v_or_b32_e32 v33, 9, v32
	v_or_b32_e32 v2, v40, v3
	v_cmp_gt_u32_e64 s[18:19], v33, v30
	v_or_b32_e32 v33, 10, v32
	v_lshl_or_b32 v82, v2, 10, v38
	v_cmp_gt_u32_e64 s[20:21], v33, v30
	v_or_b32_e32 v33, 11, v32
	v_add_u32_e32 v84, v82, v87
	v_cmp_gt_u32_e64 s[22:23], v33, v30
	v_or_b32_e32 v33, 16, v32
	v_add_u32_e32 v2, v84, v87
	v_cmp_gt_u32_e64 s[24:25], v33, v30
	v_or_b32_e32 v33, 17, v32
	v_add_u32_e32 v4, v2, v87
	v_cmp_gt_u32_e64 s[26:27], v33, v30
	v_or_b32_e32 v33, 18, v32
	v_add_u32_e32 v6, v4, v87
	v_cmp_gt_u32_e64 s[28:29], v33, v30
	v_or_b32_e32 v33, 19, v32
	v_add_u32_e32 v8, v6, v87
	v_cmp_gt_u32_e64 s[30:31], v33, v30
	v_or_b32_e32 v33, 24, v32
	v_add_u32_e32 v10, v8, v87
	v_cmp_gt_u32_e64 s[34:35], v33, v30
	v_or_b32_e32 v33, 25, v32
	v_add_u32_e32 v12, v10, v87
	v_cmp_gt_u32_e64 s[8:9], v32, v30
	v_cmp_lt_u32_e64 s[10:11], v32, v30
	v_cmp_gt_u32_e64 s[36:37], v33, v30
	v_or_b32_e32 v33, 26, v32
	v_or_b32_e32 v32, 27, v32
	v_mov_b32_e32 v85, 0
	v_add_u32_e32 v14, v12, v87
	v_cmp_gt_u32_e64 s[38:39], v33, v30
	v_cmp_gt_u32_e64 s[40:41], v32, v30
	v_mov_b32_e32 v32, 0x7c00000
	v_mov_b32_e32 v33, 0x5c00000
	v_add_u32_e32 v16, v14, v87
	v_mul_u32_u24_e32 v139, 0x50, v30
	v_mul_u32_u24_e32 v42, 0x110, v30
	v_lshlrev_b32_e32 v30, 3, v1
	v_cndmask_b32_e64 v32, v32, v33, s[4:5]
	v_mov_b32_e32 v33, v85
	v_add_u32_e32 v18, v16, v87
	v_mov_b32_e32 v34, 0xfffffef0
	v_mov_b32_e32 v35, 0x110
	v_and_b32_e32 v44, 0x78, v30
	v_lshl_add_u64 v[88:89], s[66:67], 0, v[32:33]
	v_lshlrev_b32_e32 v32, 2, v38
	v_add_u32_e32 v20, v18, v87
	v_cndmask_b32_e64 v142, v34, v35, s[4:5]
	v_lshlrev_b32_e32 v30, 1, v44
	v_lshl_or_b32 v34, v31, 11, v32
	v_mov_b32_e32 v35, v85
	v_add_u32_e32 v22, v20, v87
	v_cmp_eq_u32_e64 s[6:7], 0, v31
	v_lshlrev_b32_e32 v136, 5, v31
	v_lshlrev_b32_e32 v141, 3, v31
	v_mul_u32_u24_e32 v43, 0x1100, v31
	v_add_u32_e32 v45, s42, v30
	v_lshl_add_u64 v[36:37], s[66:67], 0, v[34:35]
	s_mov_b64 s[42:43], 0x1c00000
	v_cndmask_b32_e64 v31, 0, v39, s[4:5]
	v_add_u32_e32 v24, v22, v87
	s_add_u32 s55, s66, 0x9c00000
	v_lshl_add_u64 v[90:91], v[36:37], 0, s[42:43]
	v_lshl_add_u64 v[32:33], s[66:67], 0, v[32:33]
	s_mov_b64 s[42:43], 0x1b80000
	v_or_b32_e32 v31, v31, v143
	v_mov_b32_e32 v3, v85
	v_add_u32_e32 v26, v24, v87
	v_lshrrev_b32_e32 v159, 4, v1
	s_addc_u32 s57, s67, 0
	v_lshl_add_u64 v[92:93], v[32:33], 0, s[42:43]
	v_mad_u32_u24 v160, v31, s33, v86
	v_lshl_add_u64 v[32:33], s[64:65], 0, v[34:35]
	s_mov_b64 s[42:43], 0x4000000
	v_readlane_b32 s80, v240, 6
	v_mov_b32_e32 v31, v85
	v_mov_b32_e32 v5, v85
	v_mov_b32_e32 v7, v85
	v_mov_b32_e32 v9, v85
	v_mov_b32_e32 v11, v85
	v_mov_b32_e32 v13, v85
	v_mov_b32_e32 v15, v85
	v_mov_b32_e32 v17, v85
	v_mov_b32_e32 v19, v85
	v_mov_b32_e32 v21, v85
	v_mov_b32_e32 v23, v85
	v_mov_b32_e32 v25, v85
	v_mov_b32_e32 v27, v85
	v_add_u32_e32 v28, v26, v87
	v_mov_b32_e32 v29, v85
	v_mul_u32_u24_e32 v46, 0x110, v159
	s_add_u32 s76, s66, 0x3c00000
	v_lshl_add_u64 v[94:95], v[32:33], 0, s[42:43]
	v_lshlrev_b32_e32 v32, 2, v44
	v_mov_b32_e32 v33, v85
	v_readlane_b32 s81, v240, 7
	v_readlane_b32 s82, v240, 8
	v_readlane_b32 s83, v240, 9
	v_readlane_b32 s84, v240, 10
	v_readlane_b32 s85, v240, 11
	v_readlane_b32 s86, v240, 12
	v_readlane_b32 s87, v240, 13
	v_readlane_b32 s88, v240, 14
	v_readlane_b32 s89, v240, 15
	v_readlane_b32 s90, v240, 16
	v_readlane_b32 s91, v240, 17
	v_readlane_b32 s92, v240, 18
	v_readlane_b32 s93, v240, 19
	v_readlane_b32 s94, v240, 20
	v_readlane_b32 s95, v240, 21
	v_lshl_add_u64 v[30:31], s[66:67], 0, v[30:31]
	s_mov_b64 s[42:43], 0xbc00000
	v_lshlrev_b64 v[102:103], 1, v[2:3]
	v_mbcnt_lo_u32_b32 v2, -1, 0
	s_mov_b32 s53, 0
	v_mul_i32_i24_e32 v138, 0xffffffb4, v38
	v_lshlrev_b32_e32 v144, 1, v142
	v_mul_i32_i24_e32 v145, 3, v142
	v_lshlrev_b32_e32 v146, 3, v142
	v_mul_i32_i24_e32 v147, 9, v142
	v_mul_i32_i24_e32 v148, 10, v142
	v_mul_i32_i24_e32 v149, 11, v142
	v_lshlrev_b32_e32 v150, 4, v142
	v_mul_i32_i24_e32 v151, 17, v142
	v_mul_i32_i24_e32 v152, 18, v142
	v_mul_i32_i24_e32 v153, 19, v142
	v_mul_i32_i24_e32 v154, 24, v142
	v_mul_i32_i24_e32 v155, 25, v142
	v_mul_i32_i24_e32 v156, 26, v142
	v_mul_i32_i24_e32 v157, 27, v142
	v_lshlrev_b32_e32 v158, 3, v83
	s_addc_u32 s77, s67, 0
	v_lshl_add_u64 v[96:97], s[82:83], 0, v[32:33]
	v_lshl_add_u64 v[98:99], v[30:31], 0, s[42:43]
	v_lshl_or_b32 v161, v40, 10, v38
	s_movk_i32 s78, 0x2000
	s_movk_i32 s79, 0x3000
	s_movk_i32 s80, 0x4000
	s_movk_i32 s81, 0x5000
	s_movk_i32 s82, 0x6000
	s_movk_i32 s83, 0x7000
	s_mov_b32 s84, 0x8000
	s_mov_b32 s85, 0x9000
	s_mov_b32 s86, 0xa000
	s_mov_b32 s87, 0xb000
	s_mov_b32 s88, 0xc000
	s_mov_b32 s89, 0xd000
	s_mov_b32 s90, 0xe000
	s_mov_b32 s91, 0xf000
	v_add_u32_e32 v162, v45, v46
	s_mov_b32 s92, 0x10000
	s_mov_b32 s93, 0x30000
	s_brev_b32 s54, 60
	s_mov_b32 s56, 0x358637bd
	s_mov_b32 s94, 0x800000
	s_mov_b32 s95, 0x50000
	v_lshlrev_b64 v[100:101], 1, v[84:85]
	v_lshlrev_b64 v[104:105], 1, v[4:5]
	v_lshlrev_b64 v[106:107], 1, v[6:7]
	v_lshlrev_b64 v[108:109], 1, v[8:9]
	v_lshlrev_b64 v[110:111], 1, v[10:11]
	v_lshlrev_b64 v[112:113], 1, v[12:13]
	v_lshlrev_b64 v[114:115], 1, v[14:15]
	v_lshlrev_b64 v[116:117], 1, v[16:17]
	v_lshlrev_b64 v[118:119], 1, v[18:19]
	v_lshlrev_b64 v[120:121], 1, v[20:21]
	v_lshlrev_b64 v[122:123], 1, v[22:23]
	v_lshlrev_b64 v[124:125], 1, v[24:25]
	v_lshlrev_b64 v[126:127], 1, v[26:27]
	v_lshlrev_b64 v[128:129], 1, v[28:29]
	v_mbcnt_hi_u32_b32 v163, -1, v2
	v_add_u32_e32 v164, v41, v43
	v_add_u32_e32 v165, v137, v42
	v_cmp_gt_u32_e32 vcc, 0x100, v1
	s_cbranch_vccnz .Lprio_p5
	s_setprio 1
.Lprio_p5:
	s_mov_b32 s96, s2
	s_mov_b32 s32, s70
	s_cmpk_lg_u32 s70, 0x100
	s_cbranch_scc1 .Lp5_order
	s_bitcmp1_b32 s2, 3
	s_cbranch_scc0 .Lp5_order
	s_addk_i32 s96, 0x100
	s_movk_i32 s32, 0xff00

.LBB0_753:
	s_setprio 0
	v_readlane_b32 s0, v240, 22
	v_readlane_b32 s1, v240, 23
	s_load_dwordx16 s[4:19], s[0:1], 0x0
	s_mov_b64 s[96:97], s[72:73]
	s_waitcnt lgkmcnt(0)
	s_mov_b64 s[56:57], s[8:9]

.LBB0_897:
	s_cmp_lt_i32 s68, 8
	s_cselect_b64 s[6:7], -1, 0
	s_and_b64 s[48:49], s[6:7], s[4:5]
	s_andn2_b64 vcc, exec, s[48:49]
	s_cbranch_vccnz .LBB0_941
	s_cmpk_gt_i32 s2, 0xff
	s_cbranch_scc1 .LBB0_941
	v_cmp_gt_u32_e32 vcc, 0x100, v1
	s_cbranch_vccnz .Lprio_p7
	s_setprio 1

.LBB0_941:
	s_setprio 0
	s_cmp_gt_i32 s69, 8
	s_cselect_b64 s[4:5], -1, 0
	s_and_b64 s[6:7], s[48:49], s[4:5]
	s_andn2_b64 vcc, exec, s[6:7]
	s_cbranch_vccnz .LBB0_1009
	s_cmpk_lt_u32 s69, 0x3e9
	s_mov_b64 s[6:7], -1
	s_cbranch_scc0 .LBB0_996
	s_waitcnt vmcnt(0)
	s_waitcnt vmcnt(0)
	s_barrier
	s_mov_b64 s[6:7], exec
	v_readlane_b32 s8, v240, 4
	v_readlane_b32 s9, v240, 5
	s_and_b64 s[8:9], s[6:7], s[8:9]
	s_mov_b64 exec, s[8:9]
	s_cbranch_execz .LBB0_995
	s_add_i32 s8, 0, 0x26000
	v_mov_b32_e32 v2, s8
	s_waitcnt vmcnt(0) expcnt(0) lgkmcnt(0)
	ds_read_b32 v4, v2
	s_add_i32 s8, 0, 0x26004
	v_mov_b32_e32 v2, s8
	ds_read_b32 v2, v2
	s_waitcnt lgkmcnt(1)
	v_cmp_ne_u32_e32 vcc, 0, v4
	s_cbranch_vccnz .LBB0_959
	s_load_dword s8, s[0:1], 0x110
	s_mov_b32 s44, 1
	v_mov_b32_e32 v18, 0
	s_waitcnt lgkmcnt(0)
	s_mul_i32 s33, s71, s8
	s_add_u32 s8, s66, 0x1bc0200
	s_addc_u32 s9, s67, 0
	s_add_u32 s10, s66, 0x1bc0400
	s_addc_u32 s11, s67, 0
	s_add_u32 s12, s66, 0x1bc0500
	s_addc_u32 s13, s67, 0
	s_add_u32 s14, s66, 0x1bc0600
	s_addc_u32 s15, s67, 0
	s_add_u32 s16, s66, 0x1bc0700
	s_addc_u32 s17, s67, 0
	s_add_u32 s18, s66, 0x1bc0800
	s_addc_u32 s19, s67, 0
	s_add_u32 s20, s66, 0x1bc0900
	s_addc_u32 s21, s67, 0
	s_add_u32 s22, s66, 0x1bc0a00
	s_addc_u32 s23, s67, 0
	s_add_u32 s24, s66, 0x1bc0b00
	s_addc_u32 s25, s67, 0
	s_add_u32 s26, s66, 0x1bc0c00
	s_addc_u32 s27, s67, 0
	s_add_u32 s28, s66, 0x1bc0d00
	s_addc_u32 s29, s67, 0
	s_add_u32 s30, s66, 0x1bc0e00
	s_addc_u32 s31, s67, 0
	s_add_u32 s34, s66, 0x1bc0f00
	s_addc_u32 s35, s67, 0
	s_add_u32 s36, s66, 0x1bc1000
	s_addc_u32 s37, s67, 0
	s_add_u32 s38, s66, 0x1bc1100
	s_addc_u32 s39, s67, 0
	s_add_u32 s40, s66, 0x1bc1200
	s_addc_u32 s41, s67, 0
	s_add_u32 s42, s66, 0x1bc1300
	s_mul_i32 s33, s33, s70
	s_addc_u32 s43, s67, 0
	s_branch .LBB0_947
